# NSA selected-block loop: tile loads use a scalar tile base plus fixed per-lane offsets (no per-step address VALU)
# speedup vs baseline: 1.0042x; 1.0042x over previous
; template <bool MLA> DI void tile_gload(TileRegs& R, const bf16_t* kp, size_t kst, const bf16_t* vp, size_t vst, const bf16_t* k2p, int kb, int tid) {
;     const int key = tid >> 3, c = tid & 7;
;     R.k = *(const u32x4*)(kp + (size_t)(kb + key) * kst + 8 * c);
;     R.v = *(const u32x4*)(vp + (size_t)(kb + (tid & 63)) * vst + 8 * (tid >> 6));
;     if (MLA) R.k2 = *(const u32x4*)(k2p + (size_t)(kb + ((tid & 255) >> 2)) * 32 + 8 * (tid & 3));
; }
.LBB0_1428:
	v_readfirstlane_b32 s52, v138
	s_lshl_b32 s24, s42, 1
	s_add_u32 s24, s22, s24
	s_addc_u32 s25, s23, 0
	v_ashrrev_i32_e32 v250, 3, v214
	v_add_u32_e32 v236, s96, v250
	v_ashrrev_i32_e32 v237, 31, v236
	v_lshlrev_b64 v[236:237], 12, v[236:237]
	v_lshlrev_b32_e32 v238, 4, v214
	v_and_b32_e32 v238, 0x70, v238
	v_mov_b32_e32 v239, 0
	v_lshl_add_u64 v[236:237], s[24:25], 0, v[236:237]
	v_lshl_add_u64 v[236:237], v[236:237], 0, v[238:239]
	v_and_b32_e32 v248, 63, v214
	v_or_b32_e32 v248, s96, v248
	v_lshlrev_b32_e32 v248, 12, v248
	v_mov_b32_e32 v249, 0
	v_and_b32_e32 v250, -8, v250
	v_lshlrev_b32_e32 v250, 1, v250
	v_mov_b32_e32 v251, 0
	v_lshl_add_u64 v[248:249], s[24:25], 0, v[248:249]
	v_lshl_add_u64 v[248:249], v[248:249], 0, v[250:251]
	global_load_dwordx4 v[240:243], v[236:237], off offset:3072
	global_load_dwordx4 v[244:247], v[248:249], off offset:3840
	v_lshrrev_b32_e32 v249, 3, v214
	v_and_b32_e32 v250, 7, v214
	v_lshlrev_b32_e32 v250, 4, v250
	v_lshl_add_u32 v249, v249, 12, v250
	v_lshrrev_b32_e32 v250, 3, v214
	v_and_b32_e32 v250, -8, v250
	v_lshlrev_b32_e32 v250, 1, v250
	v_and_b32_e32 v251, 63, v214
	v_lshl_add_u32 v250, v251, 12, v250
	v_cvt_f32_i32_e32 v140, v139
	v_mul_f32_e32 v140, v186, v140
	v_fmamk_f32 v160, v186, 0x3f800000, v140
	v_fmamk_f32 v170, v186, 0x40000000, v140
	v_fmamk_f32 v171, v186, 0x40400000, v140
	v_fmamk_f32 v176, v186, 0x41000000, v140
	v_fmamk_f32 v177, v186, 0x41100000, v140
	v_fmamk_f32 v187, v186, 0x41200000, v140
	v_fmamk_f32 v188, v186, 0x41300000, v140
	v_fmamk_f32 v189, v186, 0x41800000, v140
	v_fmamk_f32 v190, v186, 0x41880000, v140
	v_fmamk_f32 v191, v186, 0x41900000, v140
	v_fmamk_f32 v192, v186, 0x41980000, v140
	v_fmamk_f32 v193, v186, 0x41c00000, v140
	v_fmamk_f32 v194, v186, 0x41c80000, v140
	v_fmamk_f32 v195, v186, 0x41d00000, v140
	v_fmamk_f32 v196, v186, 0x41d80000, v140
	v_fmamk_f32 v197, v186, 0x42000000, v140
	v_fmamk_f32 v198, v186, 0x42040000, v140
	v_fmamk_f32 v199, v186, 0x42080000, v140
	v_fmamk_f32 v207, v186, 0x420c0000, v140
	v_fmamk_f32 v210, v186, 0x42200000, v140
	v_fmamk_f32 v211, v186, 0x42240000, v140
	v_fmamk_f32 v212, v186, 0x42280000, v140
	v_fmamk_f32 v213, v186, 0x422c0000, v140
	v_fmamk_f32 v233, v186, 0x42400000, v140
	v_fmamk_f32 v234, v186, 0x42440000, v140
	v_fmamk_f32 v235, v186, 0x42480000, v140
	v_fmamk_f32 v236, v186, 0x424c0000, v140
	v_fmamk_f32 v237, v186, 0x42600000, v140
	v_fmamk_f32 v238, v186, 0x42640000, v140
	v_fmamk_f32 v239, v186, 0x42680000, v140
	v_fmamk_f32 v248, v186, 0x426c0000, v140

; template <bool MLA> DI void tile_gload(TileRegs& R, const bf16_t* kp, size_t kst, const bf16_t* vp, size_t vst, const bf16_t* k2p, int kb, int tid) {
;     const int key = tid >> 3, c = tid & 7;
;     R.k = *(const u32x4*)(kp + (size_t)(kb + key) * kst + 8 * c);
;     R.v = *(const u32x4*)(vp + (size_t)(kb + (tid & 63)) * vst + 8 * (tid >> 6));
;     if (MLA) R.k2 = *(const u32x4*)(k2p + (size_t)(kb + ((tid & 255) >> 2)) * 32 + 8 * (tid & 3));
; }
.Lsel_nn0:
	s_cmp_lt_i32 s17, 0
	s_cselect_b32 s24, s43, s17
	s_lshl_b32 s46, s42, 1
	s_add_u32 s46, s22, s46
	s_addc_u32 s47, s23, 0
	s_lshl_b32 s24, s24, 12
	s_add_u32 s46, s46, s24
	s_addc_u32 s47, s47, 0
	global_load_dwordx4 v[6:9], v249, s[46:47] offset:2816
	global_load_dwordx4 v[2:5], v250, s[46:47] offset:3584
	s_lshr_b32 s24, s43, 6
	v_lshrrev_b64 v[14:15], s24, v[120:121]
	v_and_b32_e32 v14, 1, v14
	v_cmp_eq_u32_e32 vcc, 1, v14
	s_cbranch_vccz .Lsel_skip0
	ds_read_b128 v[126:129], v161 offset:0
	ds_read_b128 v[130:133], v161 offset:4608
	ds_read_b128 v[164:167], v161 offset:32
	ds_read_b128 v[10:13], v161 offset:4640
	s_waitcnt lgkmcnt(3)
	v_mfma_f32_32x32x16_bf16 v[96:111], v[126:129], v[144:147], 0
	ds_read_b128 v[126:129], v161 offset:64
	s_waitcnt lgkmcnt(3)
	v_mfma_f32_32x32x16_bf16 v[80:95], v[130:133], v[144:147], 0
	ds_read_b128 v[130:133], v161 offset:4672
	s_waitcnt lgkmcnt(3)
	v_mfma_f32_32x32x16_bf16 v[96:111], v[164:167], v[148:151], v[96:111]
	ds_read_b128 v[164:167], v161 offset:96
	s_waitcnt lgkmcnt(3)
	v_mfma_f32_32x32x16_bf16 v[80:95], v[10:13], v[148:151], v[80:95]
	ds_read_b128 v[10:13], v161 offset:4704
	s_waitcnt lgkmcnt(3)
	v_mfma_f32_32x32x16_bf16 v[96:111], v[126:129], v[152:155], v[96:111]
	s_waitcnt lgkmcnt(2)
	v_mfma_f32_32x32x16_bf16 v[80:95], v[130:133], v[152:155], v[80:95]
	s_waitcnt lgkmcnt(1)
	v_mfma_f32_32x32x16_bf16 v[96:111], v[164:167], v[156:159], v[96:111]
	s_waitcnt lgkmcnt(0)
	v_mfma_f32_32x32x16_bf16 v[80:95], v[10:13], v[156:159], v[80:95]
	v_sub_u32_e32 v163, s43, v205
	v_cvt_f32_i32_e32 v163, v163
	v_mul_f32_e32 v134, v186, v163
	v_cndmask_b32_e32 v134, v225, v134, vcc
	s_nop 7
	v_fma_f32 v96, v96, s84, v140
	v_fma_f32 v97, v97, s84, v160
	v_fma_f32 v98, v98, s84, v170
	v_fma_f32 v99, v99, s84, v171
	v_fma_f32 v100, v100, s84, v176
	v_fma_f32 v101, v101, s84, v177
	v_fma_f32 v102, v102, s84, v187
	v_fma_f32 v103, v103, s84, v188
	v_fma_f32 v104, v104, s84, v189
	v_fma_f32 v105, v105, s84, v190
	v_fma_f32 v106, v106, s84, v191
	v_fma_f32 v107, v107, s84, v192
	v_fma_f32 v108, v108, s84, v193
	v_fma_f32 v109, v109, s84, v194
	v_fma_f32 v110, v110, s84, v195
	v_fma_f32 v111, v111, s84, v196
	v_fma_f32 v80, v80, s84, v197
	v_fma_f32 v81, v81, s84, v198
	v_fma_f32 v82, v82, s84, v199
	v_fma_f32 v83, v83, s84, v207
	v_fma_f32 v84, v84, s84, v210
	v_fma_f32 v85, v85, s84, v211
	v_fma_f32 v86, v86, s84, v212
	v_fma_f32 v87, v87, s84, v213
	v_fma_f32 v88, v88, s84, v233
	v_fma_f32 v89, v89, s84, v234
	v_fma_f32 v90, v90, s84, v235
	v_fma_f32 v91, v91, s84, v236
	v_fma_f32 v92, v92, s84, v237
	v_fma_f32 v93, v93, s84, v238
	v_fma_f32 v94, v94, s84, v239
	v_fma_f32 v95, v95, s84, v248
	s_add_i32 s24, s43, 63
	s_cmp_gt_i32 s24, s52
	s_cbranch_scc1 .Lsel_mask0

; template <bool MLA> DI void tile_gload(TileRegs& R, const bf16_t* kp, size_t kst, const bf16_t* vp, size_t vst, const bf16_t* k2p, int kb, int tid) {
;     const int key = tid >> 3, c = tid & 7;
;     R.k = *(const u32x4*)(kp + (size_t)(kb + key) * kst + 8 * c);
;     R.v = *(const u32x4*)(vp + (size_t)(kb + (tid & 63)) * vst + 8 * (tid >> 6));
;     if (MLA) R.k2 = *(const u32x4*)(k2p + (size_t)(kb + ((tid & 255) >> 2)) * 32 + 8 * (tid & 3));
; }
.Lsel_nn1:
	s_cmp_lt_i32 s17, 0
	s_cselect_b32 s24, s43, s17
	s_lshl_b32 s46, s42, 1
	s_add_u32 s46, s22, s46
	s_addc_u32 s47, s23, 0
	s_lshl_b32 s24, s24, 12
	s_add_u32 s46, s46, s24
	s_addc_u32 s47, s47, 0
	global_load_dwordx4 v[116:119], v249, s[46:47] offset:2816
	global_load_dwordx4 v[112:115], v250, s[46:47] offset:3584
	s_lshr_b32 s24, s43, 6
	v_lshrrev_b64 v[14:15], s24, v[120:121]
	v_and_b32_e32 v14, 1, v14
	v_cmp_eq_u32_e32 vcc, 1, v14
	s_cbranch_vccz .Lsel_skip1
	ds_read_b128 v[126:129], v161 offset:13312
	ds_read_b128 v[130:133], v161 offset:17920
	ds_read_b128 v[164:167], v161 offset:13344
	ds_read_b128 v[10:13], v161 offset:17952
	s_waitcnt lgkmcnt(3)
	v_mfma_f32_32x32x16_bf16 v[96:111], v[126:129], v[144:147], 0
	ds_read_b128 v[126:129], v161 offset:13376
	s_waitcnt lgkmcnt(3)
	v_mfma_f32_32x32x16_bf16 v[80:95], v[130:133], v[144:147], 0
	ds_read_b128 v[130:133], v161 offset:17984
	s_waitcnt lgkmcnt(3)
	v_mfma_f32_32x32x16_bf16 v[96:111], v[164:167], v[148:151], v[96:111]
	ds_read_b128 v[164:167], v161 offset:13408
	s_waitcnt lgkmcnt(3)
	v_mfma_f32_32x32x16_bf16 v[80:95], v[10:13], v[148:151], v[80:95]
	ds_read_b128 v[10:13], v161 offset:18016
	s_waitcnt lgkmcnt(3)
	v_mfma_f32_32x32x16_bf16 v[96:111], v[126:129], v[152:155], v[96:111]
	s_waitcnt lgkmcnt(2)
	v_mfma_f32_32x32x16_bf16 v[80:95], v[130:133], v[152:155], v[80:95]
	s_waitcnt lgkmcnt(1)
	v_mfma_f32_32x32x16_bf16 v[96:111], v[164:167], v[156:159], v[96:111]
	s_waitcnt lgkmcnt(0)
	v_mfma_f32_32x32x16_bf16 v[80:95], v[10:13], v[156:159], v[80:95]
	v_sub_u32_e32 v163, s43, v205
	v_cvt_f32_i32_e32 v163, v163
	v_mul_f32_e32 v134, v186, v163
	v_cndmask_b32_e32 v134, v225, v134, vcc
	s_nop 7
	v_fma_f32 v96, v96, s84, v140
	v_fma_f32 v97, v97, s84, v160
	v_fma_f32 v98, v98, s84, v170
	v_fma_f32 v99, v99, s84, v171
	v_fma_f32 v100, v100, s84, v176
	v_fma_f32 v101, v101, s84, v177
	v_fma_f32 v102, v102, s84, v187
	v_fma_f32 v103, v103, s84, v188
	v_fma_f32 v104, v104, s84, v189
	v_fma_f32 v105, v105, s84, v190
	v_fma_f32 v106, v106, s84, v191
	v_fma_f32 v107, v107, s84, v192
	v_fma_f32 v108, v108, s84, v193
	v_fma_f32 v109, v109, s84, v194
	v_fma_f32 v110, v110, s84, v195
	v_fma_f32 v111, v111, s84, v196
	v_fma_f32 v80, v80, s84, v197
	v_fma_f32 v81, v81, s84, v198
	v_fma_f32 v82, v82, s84, v199
	v_fma_f32 v83, v83, s84, v207
	v_fma_f32 v84, v84, s84, v210
	v_fma_f32 v85, v85, s84, v211
	v_fma_f32 v86, v86, s84, v212
	v_fma_f32 v87, v87, s84, v213
	v_fma_f32 v88, v88, s84, v233
	v_fma_f32 v89, v89, s84, v234
	v_fma_f32 v90, v90, s84, v235
	v_fma_f32 v91, v91, s84, v236
	v_fma_f32 v92, v92, s84, v237
	v_fma_f32 v93, v93, s84, v238
	v_fma_f32 v94, v94, s84, v239
	v_fma_f32 v95, v95, s84, v248
	s_add_i32 s24, s43, 63
	s_cmp_gt_i32 s24, s52
	s_cbranch_scc1 .Lsel_mask1
